# W_uv re-laid out in place once per launch (workgroup 0 before the prep phase) into per-lane MFMA operand order: DSA epilogue reads it with lane-linear 16-byte loads, no lane-half exchanges
# speedup vs baseline: 1.0315x; 1.0007x over previous
; #define LAS __attribute__((address_space(3)))
; #define GAS __attribute__((address_space(1)))
; __device__ __forceinline__ f32x16 mfma32(bf16x8 a, bf16x8 b, f32x16 c) { return __builtin_amdgcn_mfma_f32_32x32x16_bf16(a, b, c, 0, 0, 0); }
; __device__ __forceinline__ void prep_unit(const Args& a, LAS unsigned char* lds, int b, int kt, int tid) {
;     const GAS bf16* z = (const GAS bf16*)(a.ws + WS_Z);
;     LAS bf16* tT = (LAS bf16*)lds;
;     const int key = tid >> 3, ch = tid & 7; const size_t row = (size_t)b * SEQ + kt * 64 + key;
;     const u32x4 d0 = *(const GAS u32x4*)(z + row * ZW + ZDC + 16 * ch), d1 = *(const GAS u32x4*)(z + row * ZW + ZDC + 16 * ch + 8);
;     const u32x4 k0 = *(const GAS u32x4*)(z + row * ZW + ZIK + 8 * ch);
;     float v[16]; float ss = 0.f;
; #pragma unroll
;     for (int i = 0; i < 4; ++i) { v[2 * i] = bflo(d0[i]); v[2 * i + 1] = bfhi(d0[i]); v[8 + 2 * i] = bflo(d1[i]); v[8 + 2 * i + 1] = bfhi(d1[i]); }
; #pragma unroll
;     for (int i = 0; i < 16; ++i) ss += v[i] * v[i];
;     ss += __shfl_xor(ss, 1); ss += __shfl_xor(ss, 2); ss += __shfl_xor(ss, 4);
;     const float r = rsqrtf(ss * (1.f / 128.f) + EPS);
; __device__ __forceinline__ void dsa_unit32(const Args& a, LAS unsigned char* lds, const LAS unsigned long long* maskl, int b, int qb, int tid, int wave, int lane) {
;     ...
;     for (int vt = 0; vt < 2; ++vt) {
;         f32x16 acc;
; #pragma unroll
;         for (int i = 0; i < 16; ++i) acc[i] = 0.f;
;         const GAS bf16* wr = wuv + (size_t)(h * 64 + 32 * vt + l31) * 128 + 4 * hi;
; #pragma unroll
;         for (int ks = 0; ks < 8; ++ks) acc = mfma32(cat8(*(const GAS u32x2*)(wr + 16 * ks), *(const GAS u32x2*)(wr + 16 * ks + 8)), of[ks], acc);
.LBB0_927:
	s_or_b64 exec, exec, s[0:1]
	s_cmp_lg_u32 s89, 0
	s_cbranch_scc1 .Lwuv_done
	v_lshrrev_b32_e32 v0, 6, v252
	v_and_b32_e32 v1, 31, v252
	v_bfe_u32 v2, v252, 5, 1
	v_lshl_or_b32 v3, v0, 6, v1
	v_lshlrev_b32_e32 v3, 8, v3
	v_lshl_or_b32 v3, v2, 4, v3
	s_add_u32 s0, s80, 0xa10000
	s_addc_u32 s1, s81, 0
	v_add_u32_e32 v4, 0x2000, v3
	global_load_dwordx4 v[8:11], v3, s[0:1]
	global_load_dwordx4 v[12:15], v3, s[0:1] offset:32
	global_load_dwordx4 v[16:19], v3, s[0:1] offset:64
	global_load_dwordx4 v[20:23], v3, s[0:1] offset:96
	global_load_dwordx4 v[24:27], v3, s[0:1] offset:128
	global_load_dwordx4 v[28:31], v3, s[0:1] offset:160
	global_load_dwordx4 v[32:35], v3, s[0:1] offset:192
	global_load_dwordx4 v[36:39], v3, s[0:1] offset:224
	global_load_dwordx4 v[88:91], v4, s[0:1]
	global_load_dwordx4 v[92:95], v4, s[0:1] offset:32
	global_load_dwordx4 v[96:99], v4, s[0:1] offset:64
	global_load_dwordx4 v[100:103], v4, s[0:1] offset:96
	global_load_dwordx4 v[104:107], v4, s[0:1] offset:128
	global_load_dwordx4 v[108:111], v4, s[0:1] offset:160
	global_load_dwordx4 v[112:115], v4, s[0:1] offset:192
	global_load_dwordx4 v[116:119], v4, s[0:1] offset:224
	s_waitcnt vmcnt(0)
	v_permlane32_swap_b32_e32 v8, v10
	v_permlane32_swap_b32_e32 v9, v11
	v_permlane32_swap_b32_e32 v12, v14
	v_permlane32_swap_b32_e32 v13, v15
	v_permlane32_swap_b32_e32 v16, v18
	v_permlane32_swap_b32_e32 v17, v19
	v_permlane32_swap_b32_e32 v20, v22
	v_permlane32_swap_b32_e32 v21, v23
	v_permlane32_swap_b32_e32 v24, v26
	v_permlane32_swap_b32_e32 v25, v27
	v_permlane32_swap_b32_e32 v28, v30
	v_permlane32_swap_b32_e32 v29, v31
	v_permlane32_swap_b32_e32 v32, v34
	v_permlane32_swap_b32_e32 v33, v35
	v_permlane32_swap_b32_e32 v36, v38
	v_permlane32_swap_b32_e32 v37, v39
	v_permlane32_swap_b32_e32 v88, v90
	v_permlane32_swap_b32_e32 v89, v91
	v_permlane32_swap_b32_e32 v92, v94
	v_permlane32_swap_b32_e32 v93, v95
	v_permlane32_swap_b32_e32 v96, v98
	v_permlane32_swap_b32_e32 v97, v99
	v_permlane32_swap_b32_e32 v100, v102
	v_permlane32_swap_b32_e32 v101, v103
	v_permlane32_swap_b32_e32 v104, v106
	v_permlane32_swap_b32_e32 v105, v107
	v_permlane32_swap_b32_e32 v108, v110
	v_permlane32_swap_b32_e32 v109, v111
	v_permlane32_swap_b32_e32 v112, v114
	v_permlane32_swap_b32_e32 v113, v115
	v_permlane32_swap_b32_e32 v116, v118
	v_permlane32_swap_b32_e32 v117, v119
	v_and_b32_e32 v5, 63, v252
	v_lshlrev_b32_e32 v5, 4, v5
	v_lshl_or_b32 v5, v0, 14, v5
	v_add_u32_e32 v6, 0x1000, v5
	v_add_u32_e32 v7, 0x2000, v5
	v_add_u32_e32 v120, 0x3000, v5
	global_store_dwordx4 v5, v[8:11], s[0:1]
	global_store_dwordx4 v5, v[12:15], s[0:1] offset:1024
	global_store_dwordx4 v5, v[16:19], s[0:1] offset:2048
	global_store_dwordx4 v5, v[20:23], s[0:1] offset:3072
	global_store_dwordx4 v6, v[24:27], s[0:1]
	global_store_dwordx4 v6, v[28:31], s[0:1] offset:1024
	global_store_dwordx4 v6, v[32:35], s[0:1] offset:2048
	global_store_dwordx4 v6, v[36:39], s[0:1] offset:3072
	global_store_dwordx4 v7, v[88:91], s[0:1]
	global_store_dwordx4 v7, v[92:95], s[0:1] offset:1024
	global_store_dwordx4 v7, v[96:99], s[0:1] offset:2048
	global_store_dwordx4 v7, v[100:103], s[0:1] offset:3072
	global_store_dwordx4 v120, v[104:107], s[0:1]
	global_store_dwordx4 v120, v[108:111], s[0:1] offset:1024
	global_store_dwordx4 v120, v[112:115], s[0:1] offset:2048
	global_store_dwordx4 v120, v[116:119], s[0:1] offset:3072
	s_waitcnt vmcnt(0)
.Lwuv_done:
	v_readlane_b32 s0, v254, 7
	v_readlane_b32 s1, v254, 8
	s_and_b64 vcc, exec, s[0:1]
	s_waitcnt lgkmcnt(0)
	s_barrier
	s_cbranch_vccnz .LBB0_930
	v_mbcnt_hi_u32_b32 v2, -1, v225
	v_and_b32_e32 v4, 64, v2
	v_xor_b32_e32 v3, 1, v2
	v_add_u32_e32 v4, 64, v4
	v_cmp_lt_i32_e32 vcc, v3, v4
	v_mov_b32_e32 v1, 0
	v_lshlrev_b32_e32 v8, 4, v252
	v_cndmask_b32_e32 v3, v2, v3, vcc
	v_lshlrev_b32_e32 v18, 2, v3
	v_xor_b32_e32 v3, 2, v2
	v_cmp_lt_i32_e32 vcc, v3, v4
	v_lshrrev_b32_e32 v6, 2, v252
	v_and_b32_e32 v16, 48, v8
	v_cndmask_b32_e32 v3, v2, v3, vcc
	v_lshlrev_b32_e32 v19, 2, v3
	v_xor_b32_e32 v3, 4, v2
	v_cmp_lt_i32_e32 vcc, v3, v4
	v_lshlrev_b32_e32 v0, 4, v226
	s_mov_b64 s[4:5], 0x1b400000
	v_cndmask_b32_e32 v2, v2, v3, vcc
	v_lshlrev_b32_e32 v20, 2, v2
	v_lshlrev_b32_e32 v2, 5, v226
	v_mov_b32_e32 v3, v1
	v_lshl_add_u64 v[2:3], s[80:81], 0, v[2:3]
	v_mul_u32_u24_e32 v7, 0x90, v6
	v_lshlrev_b32_e32 v8, 1, v16
	v_lshl_add_u64 v[2:3], v[2:3], 0, s[4:5]
	v_lshl_add_u64 v[4:5], s[80:81], 0, v[0:1]
	s_mov_b64 s[4:5], 0x1c400000
	v_add3_u32 v21, 0, v7, v8
	v_lshlrev_b32_e32 v6, 12, v6
	v_mov_b32_e32 v7, v1
	s_add_u32 s2, s80, 0x8400000
	v_lshrrev_b32_e32 v15, 3, v252
	v_lshl_add_u64 v[4:5], v[4:5], 0, s[4:5]
	v_lshl_add_u64 v[6:7], s[80:81], 0, v[6:7]
	s_mov_b64 s[4:5], 0x1bc00000
	s_addc_u32 s3, s81, 0
	v_lshlrev_b32_e32 v12, 3, v226
	v_lshl_add_u32 v17, v15, 1, 0
	v_mul_u32_u24_e32 v22, 0x900, v226
	v_lshl_add_u64 v[6:7], v[6:7], 0, s[4:5]
	s_mov_b32 s4, 0x3c800000
	s_mov_b32 s1, 0
	s_lshl_b32 s8, s89, 6
	s_lshl_b32 s9, s84, 6
	s_movk_i32 s10, 0x1e00
	v_mov_b64_e32 v[8:9], s[2:3]
	v_lshlrev_b32_e32 v10, 1, v0
	v_mov_b32_e32 v11, v1
	s_mov_b64 s[2:3], 0x1800
	s_movk_i32 s11, 0x1000
	v_lshlrev_b32_e32 v12, 1, v12
	v_mov_b32_e32 v13, v1
	s_brev_b32 s5, 60
	v_mov_b32_e32 v14, 0x358637bd
	s_mov_b32 s12, 0x800000
	v_add_u32_e32 v22, v17, v22
	v_lshlrev_b32_e32 v16, 1, v16
	v_mov_b32_e32 v17, v1
	s_mov_b32 s13, s89

; #define GAS __attribute__((address_space(1)))
; __device__ __forceinline__ unsigned pk2(float lo, float hi) { f32x2_t v = {lo, hi}; bf16x2_t b = __builtin_convertvector(v, bf16x2_t); return __builtin_bit_cast(unsigned, b); }
; __device__ __forceinline__ f32x16 mfma32(bf16x8 a, bf16x8 b, f32x16 c) { return __builtin_amdgcn_mfma_f32_32x32x16_bf16(a, b, c, 0, 0, 0); }
; __device__ __forceinline__ void dsa_unit32(const Args& a, LAS unsigned char* lds, const LAS unsigned long long* maskl, int b, int qb, int tid, int wave, int lane) {
;     ...
;     l += __shfl_xor(l, 32);
;     const float il = 1.f / l;
;     bf16x8 of[8];
; #pragma unroll
;     for (int ks = 0; ks < 8; ++ks) { const int ct = ks >> 1, o8 = 8 * (ks & 1); u32x4 w;
;         w.x = pk2(O[ct][o8 + 0] * il, O[ct][o8 + 1] * il); w.y = pk2(O[ct][o8 + 2] * il, O[ct][o8 + 3] * il);
;         w.z = pk2(O[ct][o8 + 4] * il, O[ct][o8 + 5] * il); w.w = pk2(O[ct][o8 + 6] * il, O[ct][o8 + 7] * il); of[ks] = __builtin_bit_cast(bf16x8, w); }
; #pragma unroll
;     for (int vt = 0; vt < 2; ++vt) {
;         f32x16 acc;
; #pragma unroll
;         for (int i = 0; i < 16; ++i) acc[i] = 0.f;
;         const GAS bf16* wr = wuv + (size_t)(h * 64 + 32 * vt + l31) * 128 + 4 * hi;
; #pragma unroll
;         for (int ks = 0; ks < 8; ++ks) acc = mfma32(cat8(*(const GAS u32x2*)(wr + 16 * ks), *(const GAS u32x2*)(wr + 16 * ks + 8)), of[ks], acc);
.LBB0_1073:
	v_readlane_b32 s0, v254, 32
	v_readlane_b32 s1, v254, 33
	v_lshlrev_b32_e32 v92, 1, v182
	v_or_b32_e32 v90, s0, v5
	v_readlane_b32 s0, v254, 30
	v_mov_b32_e32 v93, v4
	v_readlane_b32 s1, v254, 31
	v_ashrrev_i32_e32 v91, 31, v90
	v_lshlrev_b64 v[0:1], 8, v[90:91]
	v_lshl_add_u64 v[98:99], s[0:1], 0, v[92:93]
	v_lshl_add_u64 v[96:97], v[98:99], 0, v[0:1]
	v_readlane_b32 s0, v254, 34
	v_lshlrev_b64 v[94:95], 11, v[178:179]
	v_readlane_b32 s1, v254, 35
	v_or_b32_e32 v100, 32, v90
	ds_bpermute_b32 v5, v181, v194
	v_lshl_add_u64 v[94:95], s[0:1], 0, v[94:95]
	v_lshl_add_u64 v[102:103], v[94:95], 0, v[92:93]
	v_lshl_add_u64 v[124:125], v[102:103], 0, v[92:93]
	v_and_b32_e32 v122, 63, v252
	v_lshlrev_b32_e32 v122, 4, v122
	v_lshrrev_b32_e32 v123, 6, v252
	v_lshl_or_b32 v122, v123, 14, v122
	v_add_u32_e32 v122, 0x1000, v122
	v_mov_b32_e32 v123, v4
	v_readlane_b32 s0, v254, 30
	v_readlane_b32 s1, v254, 31
	s_nop 1
	v_lshl_add_u64 v[120:121], s[0:1], 0, v[122:123]
	v_add_u32_e32 v122, 0x2000, v122
	v_lshl_add_u64 v[122:123], s[0:1], 0, v[122:123]
	global_load_dwordx4 v[0:3], v[120:121], off offset:-4096
	global_load_dwordx4 v[70:73], v[120:121], off offset:-3072
	global_load_dwordx4 v[74:77], v[120:121], off offset:-2048
	global_load_dwordx4 v[78:81], v[120:121], off offset:-1024
	global_load_dwordx4 v[82:85], v[120:121], off
	global_load_dwordx4 v[86:89], v[120:121], off offset:1024
	global_load_dwordx4 v[90:93], v[120:121], off offset:2048
	global_load_dwordx4 v[94:97], v[120:121], off offset:3072
	s_nop 0
	s_waitcnt lgkmcnt(0)
	v_add_f32_e32 v5, v194, v5
	v_div_scale_f32 v104, s[0:1], v5, v5, 1.0
	v_rcp_f32_e32 v105, v104
	v_ashrrev_i32_e32 v101, 31, v100
	v_lshlrev_b64 v[100:101], 8, v[100:101]
	v_lshl_add_u64 v[98:99], v[98:99], 0, v[100:101]
	global_load_dwordx4 v[146:149], v[122:123], off offset:-4096
	global_load_dwordx4 v[150:153], v[122:123], off offset:-3072
	global_load_dwordx4 v[154:157], v[122:123], off offset:-2048
	global_load_dwordx4 v[158:161], v[122:123], off offset:-1024
	global_load_dwordx4 v[162:165], v[122:123], off
	global_load_dwordx4 v[166:169], v[122:123], off offset:1024
	global_load_dwordx4 v[170:173], v[122:123], off offset:2048
	global_load_dwordx4 v[174:177], v[122:123], off offset:3072
	v_fma_f32 v101, -v104, v105, 1.0
	v_div_scale_f32 v100, vcc, 1.0, v5, 1.0
	v_fmac_f32_e32 v105, v101, v105
	v_mul_f32_e32 v101, v100, v105
	v_fma_f32 v106, -v104, v101, v100
	v_fmac_f32_e32 v101, v106, v105
	v_fma_f32 v100, -v104, v101, v100
	v_div_fmas_f32 v100, v100, v105, v101
	v_div_fixup_f32 v100, v100, v5, 1.0
	v_pk_mul_f32 v[54:55], v[54:55], v[100:101] op_sel_hi:[1,0]
	v_pk_mul_f32 v[56:57], v[56:57], v[100:101] op_sel_hi:[1,0]
	v_pk_mul_f32 v[58:59], v[58:59], v[100:101] op_sel_hi:[1,0]
	v_pk_mul_f32 v[60:61], v[60:61], v[100:101] op_sel_hi:[1,0]
	v_pk_mul_f32 v[112:113], v[38:39], v[100:101] op_sel_hi:[1,0]
	v_pk_mul_f32 v[114:115], v[40:41], v[100:101] op_sel_hi:[1,0]
	v_cvt_pk_bf16_f32 v38, v54, v55
	v_cvt_pk_bf16_f32 v39, v56, v57
	v_cvt_pk_bf16_f32 v40, v58, v59
	v_cvt_pk_bf16_f32 v41, v60, v61
	v_pk_mul_f32 v[104:105], v[62:63], v[100:101] op_sel_hi:[1,0]
	v_pk_mul_f32 v[106:107], v[64:65], v[100:101] op_sel_hi:[1,0]
	v_pk_mul_f32 v[108:109], v[66:67], v[100:101] op_sel_hi:[1,0]
	v_pk_mul_f32 v[110:111], v[68:69], v[100:101] op_sel_hi:[1,0]
	v_pk_mul_f32 v[116:117], v[42:43], v[100:101] op_sel_hi:[1,0]
	v_pk_mul_f32 v[118:119], v[44:45], v[100:101] op_sel_hi:[1,0]
	v_cvt_pk_bf16_f32 v42, v112, v113
	v_cvt_pk_bf16_f32 v43, v114, v115
	v_cvt_pk_bf16_f32 v44, v116, v117
	v_cvt_pk_bf16_f32 v45, v118, v119
	v_pk_mul_f32 v[46:47], v[46:47], v[100:101] op_sel_hi:[1,0]
	v_pk_mul_f32 v[48:49], v[48:49], v[100:101] op_sel_hi:[1,0]
	v_pk_mul_f32 v[50:51], v[50:51], v[100:101] op_sel_hi:[1,0]
	v_pk_mul_f32 v[52:53], v[52:53], v[100:101] op_sel_hi:[1,0]
	v_pk_mul_f32 v[30:31], v[30:31], v[100:101] op_sel_hi:[1,0]
	v_pk_mul_f32 v[32:33], v[32:33], v[100:101] op_sel_hi:[1,0]
	v_pk_mul_f32 v[34:35], v[34:35], v[100:101] op_sel_hi:[1,0]
	v_pk_mul_f32 v[36:37], v[36:37], v[100:101] op_sel_hi:[1,0]
	v_cvt_pk_bf16_f32 v30, v30, v31
	v_cvt_pk_bf16_f32 v31, v32, v33
	v_cvt_pk_bf16_f32 v32, v34, v35
	v_cvt_pk_bf16_f32 v33, v36, v37
	v_pk_mul_f32 v[6:7], v[6:7], v[100:101] op_sel_hi:[1,0]
	v_pk_mul_f32 v[8:9], v[8:9], v[100:101] op_sel_hi:[1,0]
	v_pk_mul_f32 v[10:11], v[10:11], v[100:101] op_sel_hi:[1,0]
	v_pk_mul_f32 v[12:13], v[12:13], v[100:101] op_sel_hi:[1,0]
	v_cvt_pk_bf16_f32 v34, v6, v7
	v_cvt_pk_bf16_f32 v35, v8, v9
	s_waitcnt vmcnt(8)
; #define GAS __attribute__((address_space(1)))
; __device__ __forceinline__ unsigned pk2(float lo, float hi) { f32x2_t v = {lo, hi}; bf16x2_t b = __builtin_convertvector(v, bf16x2_t); return __builtin_bit_cast(unsigned, b); }
; __device__ __forceinline__ f32x16 mfma32(bf16x8 a, bf16x8 b, f32x16 c) { return __builtin_amdgcn_mfma_f32_32x32x16_bf16(a, b, c, 0, 0, 0); }
; __device__ __forceinline__ void dsa_unit32(const Args& a, LAS unsigned char* lds, const LAS unsigned long long* maskl, int b, int qb, int tid, int wave, int lane) {
;     ...
;     for (int vt = 0; vt < 2; ++vt) {
;         f32x16 acc;
; #pragma unroll
;         for (int i = 0; i < 16; ++i) acc[i] = 0.f;
;         const GAS bf16* wr = wuv + (size_t)(h * 64 + 32 * vt + l31) * 128 + 4 * hi;
; #pragma unroll
;         for (int ks = 0; ks < 8; ++ks) acc = mfma32(cat8(*(const GAS u32x2*)(wr + 16 * ks), *(const GAS u32x2*)(wr + 16 * ks + 8)), of[ks], acc);
; #pragma unroll
;         for (int g = 0; g < 4; ++g) { u32x2 w; w.x = pk2(acc[4 * g], acc[4 * g + 1]); w.y = pk2(acc[4 * g + 2], acc[4 * g + 3]);
;             *(GAS u32x2*)(Y + (rowb + t0 + l31) * DM + 512 + h * 64 + 32 * vt + 8 * g + 4 * hi) = w; }
;     }
	s_nop 1
	v_mfma_f32_32x32x16_bf16 v[54:69], v[0:3], v[38:41], 0
	v_cvt_pk_bf16_f32 v0, v104, v105
	v_cvt_pk_bf16_f32 v1, v106, v107
	v_cvt_pk_bf16_f32 v2, v108, v109
	v_cvt_pk_bf16_f32 v3, v110, v111
	v_cvt_pk_bf16_f32 v36, v10, v11
	v_cvt_pk_bf16_f32 v37, v12, v13
	v_pk_mul_f32 v[14:15], v[14:15], v[100:101] op_sel_hi:[1,0]
	v_mfma_f32_32x32x16_bf16 v[54:69], v[70:73], v[0:3], v[54:69]
	v_mul_f32_e64 v70, v22, v100
	v_mul_f32_e64 v71, v23, v100
	v_mul_f32_e64 v72, v24, v100
	v_mul_f32_e64 v73, v25, v100
	v_cvt_pk_bf16_f32 v22, v46, v47
	v_cvt_pk_bf16_f32 v23, v48, v49
	v_cvt_pk_bf16_f32 v24, v50, v51
	v_cvt_pk_bf16_f32 v25, v52, v53
	v_pk_mul_f32 v[6:7], v[16:17], v[100:101] op_sel_hi:[1,0]
	v_mfma_f32_32x32x16_bf16 v[54:69], v[74:77], v[42:45], v[54:69]
	v_mul_f32_e64 v74, v26, v100
	v_mul_f32_e64 v75, v27, v100
	v_mul_f32_e64 v76, v28, v100
	v_mul_f32_e64 v77, v29, v100
	v_cvt_pk_bf16_f32 v26, v70, v71
	v_cvt_pk_bf16_f32 v27, v72, v73
	v_cvt_pk_bf16_f32 v28, v74, v75
	v_cvt_pk_bf16_f32 v29, v76, v77
	v_pk_mul_f32 v[8:9], v[18:19], v[100:101] op_sel_hi:[1,0]
	v_mfma_f32_32x32x16_bf16 v[54:69], v[78:81], v[22:25], v[54:69]
	v_mul_f32_e64 v10, v20, v100
	v_mul_f32_e64 v11, v21, v100
	v_cvt_pk_bf16_f32 v46, v14, v15
	v_cvt_pk_bf16_f32 v47, v6, v7
	v_cvt_pk_bf16_f32 v48, v8, v9
	v_cvt_pk_bf16_f32 v49, v10, v11
	s_mov_b64 s[0:1], 0
	v_mfma_f32_32x32x16_bf16 v[54:69], v[82:85], v[26:29], v[54:69]
	v_mfma_f32_32x32x16_bf16 v[54:69], v[86:89], v[30:33], v[54:69]
	v_mfma_f32_32x32x16_bf16 v[54:69], v[90:93], v[34:37], v[54:69]
	v_mfma_f32_32x32x16_bf16 v[54:69], v[94:97], v[46:49], v[54:69]
	s_nop 11
	v_cvt_pk_bf16_f32 v6, v54, v55
	v_cvt_pk_bf16_f32 v7, v56, v57
	v_cvt_pk_bf16_f32 v8, v58, v59
	v_cvt_pk_bf16_f32 v9, v60, v61
	v_cvt_pk_bf16_f32 v10, v62, v63
	v_cvt_pk_bf16_f32 v11, v64, v65
	v_cvt_pk_bf16_f32 v12, v66, v67
	v_cvt_pk_bf16_f32 v13, v68, v69
	v_permlane32_swap_b32_e32 v6, v8
	v_permlane32_swap_b32_e32 v7, v9
	v_permlane32_swap_b32_e32 v10, v12
	v_permlane32_swap_b32_e32 v11, v13
	global_store_dwordx4 v[124:125], v[6:9], off offset:1024
	global_store_dwordx4 v[124:125], v[10:13], off offset:1056
	s_waitcnt vmcnt(2)
	s_nop 1
	v_mfma_f32_32x32x16_bf16 v[6:21], v[146:149], v[38:41], 0
	v_mfma_f32_32x32x16_bf16 v[6:21], v[150:153], v[0:3], v[6:21]
	v_mfma_f32_32x32x16_bf16 v[6:21], v[154:157], v[42:45], v[6:21]
	v_mfma_f32_32x32x16_bf16 v[6:21], v[158:161], v[22:25], v[6:21]
	v_mfma_f32_32x32x16_bf16 v[6:21], v[162:165], v[26:29], v[6:21]
	v_mfma_f32_32x32x16_bf16 v[6:21], v[166:169], v[30:33], v[6:21]
	v_mfma_f32_32x32x16_bf16 v[6:21], v[170:173], v[34:37], v[6:21]
	v_mfma_f32_32x32x16_bf16 v[6:21], v[174:177], v[46:49], v[6:21]
	s_nop 11
	v_cvt_pk_bf16_f32 v0, v6, v7
	v_cvt_pk_bf16_f32 v1, v8, v9
	v_cvt_pk_bf16_f32 v2, v10, v11
	v_cvt_pk_bf16_f32 v3, v12, v13
	v_cvt_pk_bf16_f32 v6, v14, v15
	v_cvt_pk_bf16_f32 v7, v16, v17
	v_cvt_pk_bf16_f32 v8, v18, v19
	v_cvt_pk_bf16_f32 v9, v20, v21
	v_permlane32_swap_b32_e32 v0, v2
	v_permlane32_swap_b32_e32 v1, v3
	v_permlane32_swap_b32_e32 v6, v8
	v_permlane32_swap_b32_e32 v7, v9
	global_store_dwordx4 v[124:125], v[0:3], off offset:1088
	global_store_dwordx4 v[124:125], v[6:9], off offset:1120
